# t6 + GEMM K-loops: removed the back-to-back s_setprio 0/1 flips between the two MFMA blocks of each super-phase (32 MFMAs contiguous at prio 1)
# speedup vs baseline: 1.0046x; 1.0046x over previous
; #define PG8_STAGE(bufoff, gbase, voff) do { _Pragma("unroll") for (int _i = 0; _i < 2; ++_i) \
;         __builtin_amdgcn_global_load_lds((const unsigned*)((const char*)(gbase) + (voff)[_i]), (PG8_LAS unsigned*)(lds + (bufoff) + ldsw + _i * 8192), 16, 0, 0); } while (0)
; #define PG8_WAIT_V(n) asm volatile("s_waitcnt vmcnt(" #n ")" ::: "memory")
; #define PG8_WAIT_L(n) asm volatile("s_waitcnt lgkmcnt(" #n ")" ::: "memory")
; #define PG8_BAR __builtin_amdgcn_s_barrier()
; #define PG8_SCHED __builtin_amdgcn_sched_barrier(0)
; template <class Epi, class Sched, bool ALIGN_EPI = false, bool SP2 = false, bool F8 = false>
; __device__ __forceinline__ void gemm_phase(PG8_LAS unsigned char* lds, const Gemm g, const Sched& S, const Epi& E) {
;     ...
;             PG8_LDB(B0, 0, 0); PG8_LDB(B1, 0, 1); PG8_SCHED; PG8_LDA(At, 0, 0); PG8_STAGE(PG8_SA(1, 1), a1 + hstep, voffA);
;             PG8_WAIT_V(8); PG8_WAIT_L(0); PG8_BAR; PG8_MMA(0, 0, At, B0); PG8_MMA(0, 1, At, B1); PG8_BAR; PG8_SCHED;
;             PG8_LDA(At, 0, 1); PG8_STAGE(PG8_SB(0, 0), b2, voffB); PG8_STAGE(PG8_SB(0, 1), b2 + hstep, voffB); PG8_STAGE(PG8_SA(0, 0), a2, voffA);
;             PG8_WAIT_V(8); PG8_WAIT_L(0); PG8_BAR; PG8_MMA(1, 0, At, B0); PG8_MMA(1, 1, At, B1); PG8_BAR; PG8_SCHED;
.LBB0_73:
	ds_read_b128 v[16:19], v190
	ds_read_b128 v[20:23], v191
	ds_read_b128 v[24:27], v192
	ds_read_b128 v[28:31], v193
	ds_read_b128 v[0:3], v194
	ds_read_b128 v[4:7], v195
	ds_read_b128 v[8:11], v196
	ds_read_b128 v[12:15], v197
	s_add_u32 s28, s26, 0xfff80080
	s_addc_u32 s29, s27, -1
	s_cmp_eq_u32 s58, 28
	s_cselect_b32 s31, s5, s29
	s_cselect_b32 s30, s7, s28
	s_cselect_b32 s29, s19, s57
	s_cselect_b32 s28, s21, s56
	v_lshl_add_u64 v[232:233], s[26:27], 0, v[174:175]
	s_add_i32 m0, s35, 0xc000
	ds_read_b128 v[182:185], v206
	ds_read_b128 v[186:189], v206 offset:1024
	ds_read_b128 v[208:211], v206 offset:2048
	ds_read_b128 v[212:215], v206 offset:3072
	ds_read_b128 v[216:219], v206 offset:4096
	ds_read_b128 v[220:223], v206 offset:5120
	ds_read_b128 v[224:227], v206 offset:6144
	ds_read_b128 v[228:231], v206 offset:7168
	global_load_lds_dwordx4 v[232:233], off
	v_lshl_add_u64 v[232:233], s[26:27], 0, v[176:177]
	s_add_i32 m0, s35, 0xe000
	s_nop 0
	global_load_lds_dwordx4 v[232:233], off
	s_waitcnt vmcnt(8)
	s_waitcnt lgkmcnt(0)
	s_barrier
	s_setprio 1
	s_waitcnt lgkmcnt(0)
	v_mfma_f32_16x16x128_f8f6f4 v[156:159], v[16:23], v[182:189], v[156:159]
	v_mfma_f32_16x16x128_f8f6f4 v[152:155], v[24:31], v[182:189], v[152:155]
	v_mfma_f32_16x16x128_f8f6f4 v[140:143], v[16:23], v[208:215], v[140:143]
	v_mfma_f32_16x16x128_f8f6f4 v[136:139], v[24:31], v[208:215], v[136:139]
	v_mfma_f32_16x16x128_f8f6f4 v[124:127], v[16:23], v[216:223], v[124:127]
	v_mfma_f32_16x16x128_f8f6f4 v[120:123], v[24:31], v[216:223], v[120:123]
	v_mfma_f32_16x16x128_f8f6f4 v[108:111], v[16:23], v[224:231], v[108:111]
	v_mfma_f32_16x16x128_f8f6f4 v[104:107], v[24:31], v[224:231], v[104:107]
	v_mfma_f32_16x16x128_f8f6f4 v[148:151], v[0:7], v[182:189], v[148:151]
	v_mfma_f32_16x16x128_f8f6f4 v[144:147], v[8:15], v[182:189], v[144:147]
	v_mfma_f32_16x16x128_f8f6f4 v[132:135], v[0:7], v[208:215], v[132:135]
	v_mfma_f32_16x16x128_f8f6f4 v[128:131], v[8:15], v[208:215], v[128:131]
	v_mfma_f32_16x16x128_f8f6f4 v[116:119], v[0:7], v[216:223], v[116:119]
	v_mfma_f32_16x16x128_f8f6f4 v[112:115], v[8:15], v[216:223], v[112:115]
	v_mfma_f32_16x16x128_f8f6f4 v[100:103], v[0:7], v[224:231], v[100:103]
	v_mfma_f32_16x16x128_f8f6f4 v[96:99], v[8:15], v[224:231], v[96:99]
	s_setprio 0
	s_barrier
	s_mov_b32 m0, s36
	v_lshl_add_u64 v[182:183], s[28:29], 0, v[164:165]
	s_add_u32 s60, s28, 0x80000
	ds_read_b128 v[208:211], v206 offset:16384
	ds_read_b128 v[212:215], v206 offset:17408
	ds_read_b128 v[216:219], v206 offset:18432
	ds_read_b128 v[220:223], v206 offset:19456
	ds_read_b128 v[224:227], v206 offset:20480
	ds_read_b128 v[228:231], v206 offset:21504
	ds_read_b128 v[232:235], v206 offset:22528
	ds_read_b128 v[236:239], v206 offset:23552
	global_load_lds_dwordx4 v[182:183], off
	v_lshl_add_u64 v[184:185], s[28:29], 0, v[168:169]
	s_mov_b32 m0, s37
	s_addc_u32 s61, s29, 0
	global_load_lds_dwordx4 v[184:185], off
	v_lshl_add_u64 v[186:187], s[60:61], 0, v[164:165]
	s_mov_b32 m0, s38
	v_lshl_add_u64 v[188:189], s[30:31], 0, v[166:167]
	global_load_lds_dwordx4 v[186:187], off
	v_lshl_add_u64 v[186:187], s[60:61], 0, v[168:169]
	s_mov_b32 m0, s39
	s_nop 0
	global_load_lds_dwordx4 v[186:187], off
	v_lshl_add_u64 v[186:187], s[30:31], 0, v[160:161]
	s_mov_b32 m0, s35
	s_nop 0
	global_load_lds_dwordx4 v[186:187], off
	s_mov_b32 m0, s40
	s_nop 0
	global_load_lds_dwordx4 v[188:189], off
	s_waitcnt vmcnt(8)
	s_waitcnt lgkmcnt(0)
	s_barrier
	s_setprio 1
	s_waitcnt lgkmcnt(0)
	v_mfma_f32_16x16x128_f8f6f4 v[92:95], v[16:23], v[208:215], v[92:95]
	v_mfma_f32_16x16x128_f8f6f4 v[88:91], v[24:31], v[208:215], v[88:91]
	v_mfma_f32_16x16x128_f8f6f4 v[76:79], v[16:23], v[216:223], v[76:79]
	v_mfma_f32_16x16x128_f8f6f4 v[72:75], v[24:31], v[216:223], v[72:75]
	v_mfma_f32_16x16x128_f8f6f4 v[60:63], v[16:23], v[224:231], v[60:63]
	v_mfma_f32_16x16x128_f8f6f4 v[56:59], v[24:31], v[224:231], v[56:59]
	v_mfma_f32_16x16x128_f8f6f4 v[44:47], v[16:23], v[232:239], v[44:47]
	v_mfma_f32_16x16x128_f8f6f4 v[40:43], v[24:31], v[232:239], v[40:43]
	v_mfma_f32_16x16x128_f8f6f4 v[84:87], v[0:7], v[208:215], v[84:87]
	v_mfma_f32_16x16x128_f8f6f4 v[80:83], v[8:15], v[208:215], v[80:83]
	v_mfma_f32_16x16x128_f8f6f4 v[68:71], v[0:7], v[216:223], v[68:71]
	v_mfma_f32_16x16x128_f8f6f4 v[64:67], v[8:15], v[216:223], v[64:67]
	v_mfma_f32_16x16x128_f8f6f4 v[52:55], v[0:7], v[224:231], v[52:55]
	v_mfma_f32_16x16x128_f8f6f4 v[48:51], v[8:15], v[224:231], v[48:51]
	v_mfma_f32_16x16x128_f8f6f4 v[36:39], v[0:7], v[232:239], v[36:39]
	v_mfma_f32_16x16x128_f8f6f4 v[32:35], v[8:15], v[232:239], v[32:35]
	s_setprio 0
	s_barrier
; #define PG8_STAGE(bufoff, gbase, voff) do { _Pragma("unroll") for (int _i = 0; _i < 2; ++_i) \
;         __builtin_amdgcn_global_load_lds((const unsigned*)((const char*)(gbase) + (voff)[_i]), (PG8_LAS unsigned*)(lds + (bufoff) + ldsw + _i * 8192), 16, 0, 0); } while (0)
; #define PG8_WAIT_V(n) asm volatile("s_waitcnt vmcnt(" #n ")" ::: "memory")
; #define PG8_WAIT_L(n) asm volatile("s_waitcnt lgkmcnt(" #n ")" ::: "memory")
; #define PG8_BAR __builtin_amdgcn_s_barrier()
; #define PG8_SCHED __builtin_amdgcn_sched_barrier(0)
; template <class Epi, class Sched, bool ALIGN_EPI = false, bool SP2 = false, bool F8 = false>
; __device__ __forceinline__ void gemm_phase(PG8_LAS unsigned char* lds, const Gemm g, const Sched& S, const Epi& E) {
;     ...
;             PG8_LDB(B0, 1, 0); PG8_LDB(B1, 1, 1); PG8_SCHED; PG8_LDA(At, 1, 0); PG8_STAGE(PG8_SA(0, 1), a2 + hstep, voffA);
;             PG8_WAIT_V(8); PG8_WAIT_L(0); PG8_BAR; PG8_MMA(0, 0, At, B0); PG8_MMA(0, 1, At, B1); PG8_BAR; PG8_SCHED;
;             PG8_LDA(At, 1, 1); PG8_STAGE(PG8_SB(1, 0), b3, voffB); PG8_STAGE(PG8_SB(1, 1), b3 + hstep, voffB); PG8_STAGE(PG8_SA(1, 0), a3, voffA);
;             PG8_WAIT_V(8); PG8_WAIT_L(0); PG8_BAR; PG8_MMA(1, 0, At, B0); PG8_MMA(1, 1, At, B1); PG8_BAR; PG8_SCHED;
	ds_read_b128 v[0:3], v198
	ds_read_b128 v[4:7], v199
	ds_read_b128 v[8:11], v200
	ds_read_b128 v[12:15], v201
	ds_read_b128 v[16:19], v202
	ds_read_b128 v[20:23], v203
	ds_read_b128 v[24:27], v204
	ds_read_b128 v[28:31], v205
	s_add_u32 s30, s30, 0x80000
	s_addc_u32 s31, s31, 0
	s_mov_b32 m0, s41
	v_lshl_add_u64 v[240:241], s[30:31], 0, v[160:161]
	ds_read_b128 v[208:211], v206 offset:32768
	ds_read_b128 v[212:215], v206 offset:33792
	ds_read_b128 v[216:219], v206 offset:34816
	ds_read_b128 v[220:223], v206 offset:35840
	ds_read_b128 v[224:227], v206 offset:36864
	ds_read_b128 v[228:231], v206 offset:37888
	ds_read_b128 v[232:235], v206 offset:38912
	ds_read_b128 v[236:239], v206 offset:39936
	global_load_lds_dwordx4 v[240:241], off
	v_lshl_add_u64 v[240:241], s[30:31], 0, v[166:167]
	s_mov_b32 m0, s42
	s_nop 0
	global_load_lds_dwordx4 v[240:241], off
	s_waitcnt vmcnt(8)
	s_waitcnt lgkmcnt(0)
	s_barrier
	s_setprio 1
	s_waitcnt lgkmcnt(0)
	v_mfma_f32_16x16x128_f8f6f4 v[156:159], v[0:7], v[208:215], v[156:159]
	v_mfma_f32_16x16x128_f8f6f4 v[152:155], v[8:15], v[208:215], v[152:155]
	v_mfma_f32_16x16x128_f8f6f4 v[140:143], v[0:7], v[216:223], v[140:143]
	v_mfma_f32_16x16x128_f8f6f4 v[136:139], v[8:15], v[216:223], v[136:139]
	v_mfma_f32_16x16x128_f8f6f4 v[124:127], v[0:7], v[224:231], v[124:127]
	v_mfma_f32_16x16x128_f8f6f4 v[120:123], v[8:15], v[224:231], v[120:123]
	v_mfma_f32_16x16x128_f8f6f4 v[108:111], v[0:7], v[232:239], v[108:111]
	v_mfma_f32_16x16x128_f8f6f4 v[104:107], v[8:15], v[232:239], v[104:107]
	v_mfma_f32_16x16x128_f8f6f4 v[148:151], v[16:23], v[208:215], v[148:151]
	v_mfma_f32_16x16x128_f8f6f4 v[144:147], v[24:31], v[208:215], v[144:147]
	v_mfma_f32_16x16x128_f8f6f4 v[132:135], v[16:23], v[216:223], v[132:135]
	v_mfma_f32_16x16x128_f8f6f4 v[128:131], v[24:31], v[216:223], v[128:131]
	v_mfma_f32_16x16x128_f8f6f4 v[116:119], v[16:23], v[224:231], v[116:119]
	v_mfma_f32_16x16x128_f8f6f4 v[112:115], v[24:31], v[224:231], v[112:115]
	v_mfma_f32_16x16x128_f8f6f4 v[100:103], v[16:23], v[232:239], v[100:103]
	v_mfma_f32_16x16x128_f8f6f4 v[96:99], v[24:31], v[232:239], v[96:99]
	s_setprio 0
	s_barrier
	s_mov_b32 m0, s45
	v_lshl_add_u64 v[182:183], v[182:183], 0, s[14:15]
	s_add_u32 s28, s28, 0x80080
	ds_read_b128 v[208:211], v206 offset:49152
	ds_read_b128 v[212:215], v206 offset:50176
	ds_read_b128 v[216:219], v206 offset:51200
	ds_read_b128 v[220:223], v206 offset:52224
	ds_read_b128 v[224:227], v206 offset:53248
	ds_read_b128 v[228:231], v206 offset:54272
	ds_read_b128 v[232:235], v206 offset:55296
	ds_read_b128 v[236:239], v206 offset:56320
	global_load_lds_dwordx4 v[182:183], off
	v_lshl_add_u64 v[182:183], v[184:185], 0, s[14:15]
	s_mov_b32 m0, s46
	s_addc_u32 s29, s29, 0
	global_load_lds_dwordx4 v[182:183], off
	v_lshl_add_u64 v[182:183], s[28:29], 0, v[164:165]
	s_mov_b32 m0, s49
	s_nop 0
	global_load_lds_dwordx4 v[182:183], off
	v_lshl_add_u64 v[182:183], s[28:29], 0, v[168:169]
	s_mov_b32 m0, s50
	s_nop 0
	global_load_lds_dwordx4 v[182:183], off
	v_lshl_add_u64 v[182:183], v[186:187], 0, s[14:15]
	s_mov_b32 m0, s47
	s_nop 0
	global_load_lds_dwordx4 v[182:183], off
	v_lshl_add_u64 v[182:183], v[188:189], 0, s[14:15]
	s_mov_b32 m0, s48
	s_nop 0
	global_load_lds_dwordx4 v[182:183], off
	s_waitcnt vmcnt(8)
	s_waitcnt lgkmcnt(0)
	s_barrier
	s_setprio 1
	s_waitcnt lgkmcnt(0)
	v_mfma_f32_16x16x128_f8f6f4 v[92:95], v[0:7], v[208:215], v[92:95]
	v_mfma_f32_16x16x128_f8f6f4 v[88:91], v[8:15], v[208:215], v[88:91]
	v_mfma_f32_16x16x128_f8f6f4 v[76:79], v[0:7], v[216:223], v[76:79]
	v_mfma_f32_16x16x128_f8f6f4 v[72:75], v[8:15], v[216:223], v[72:75]
	v_mfma_f32_16x16x128_f8f6f4 v[60:63], v[0:7], v[224:231], v[60:63]
	v_mfma_f32_16x16x128_f8f6f4 v[56:59], v[8:15], v[224:231], v[56:59]
	v_mfma_f32_16x16x128_f8f6f4 v[44:47], v[0:7], v[232:239], v[44:47]
	v_mfma_f32_16x16x128_f8f6f4 v[40:43], v[8:15], v[232:239], v[40:43]
	v_mfma_f32_16x16x128_f8f6f4 v[84:87], v[16:23], v[208:215], v[84:87]
	v_mfma_f32_16x16x128_f8f6f4 v[80:83], v[24:31], v[208:215], v[80:83]
	v_mfma_f32_16x16x128_f8f6f4 v[68:71], v[16:23], v[216:223], v[68:71]
	v_mfma_f32_16x16x128_f8f6f4 v[64:67], v[24:31], v[216:223], v[64:67]
	v_mfma_f32_16x16x128_f8f6f4 v[52:55], v[16:23], v[224:231], v[52:55]
	v_mfma_f32_16x16x128_f8f6f4 v[48:51], v[24:31], v[224:231], v[48:51]
	v_mfma_f32_16x16x128_f8f6f4 v[36:39], v[16:23], v[232:239], v[36:39]
	v_mfma_f32_16x16x128_f8f6f4 v[32:35], v[24:31], v[232:239], v[32:35]
	s_setprio 0
	s_barrier
	s_add_i32 s58, s58, 2
	s_add_u32 s26, s26, 0x100
	s_addc_u32 s27, s27, 0
	s_add_u32 s56, s56, 0x100
	s_addc_u32 s57, s57, 0
	s_cmp_gt_u32 s58, 29
	s_cbranch_scc0 .LBB0_73
	s_and_b64 vcc, exec, s[16:17]
	s_cbranch_vccz .LBB0_76
	s_barrier

; #define PG8_STAGE(bufoff, gbase, voff) do { _Pragma("unroll") for (int _i = 0; _i < 2; ++_i) \
;         __builtin_amdgcn_global_load_lds((const unsigned*)((const char*)(gbase) + (voff)[_i]), (PG8_LAS unsigned*)(lds + (bufoff) + ldsw + _i * 8192), 16, 0, 0); } while (0)
; #define PG8_WAIT_V(n) asm volatile("s_waitcnt vmcnt(" #n ")" ::: "memory")
; #define PG8_WAIT_L(n) asm volatile("s_waitcnt lgkmcnt(" #n ")" ::: "memory")
; #define PG8_BAR __builtin_amdgcn_s_barrier()
; #define PG8_SCHED __builtin_amdgcn_sched_barrier(0)
; template <class Epi, class Sched, bool ALIGN_EPI = false, bool SP2 = false, bool F8 = false>
; __device__ __forceinline__ void gemm_phase(PG8_LAS unsigned char* lds, const Gemm g, const Sched& S, const Epi& E) {
;     ...
;             PG8_LDB(B0, 0, 0); PG8_LDB(B1, 0, 1); PG8_SCHED; PG8_LDA(At, 0, 0); PG8_STAGE(PG8_SA(1, 1), a1 + hstep, voffA);
;             PG8_WAIT_V(8); PG8_WAIT_L(0); PG8_BAR; PG8_MMA(0, 0, At, B0); PG8_MMA(0, 1, At, B1); PG8_BAR; PG8_SCHED;
;             PG8_LDA(At, 0, 1); PG8_STAGE(PG8_SB(0, 0), b2, voffB); PG8_STAGE(PG8_SB(0, 1), b2 + hstep, voffB); PG8_STAGE(PG8_SA(0, 0), a2, voffA);
;             PG8_WAIT_V(8); PG8_WAIT_L(0); PG8_BAR; PG8_MMA(1, 0, At, B0); PG8_MMA(1, 1, At, B1); PG8_BAR; PG8_SCHED;
.LBB0_326:
	ds_read_b128 v[16:19], v182
	ds_read_b128 v[20:23], v183
	ds_read_b128 v[24:27], v184
	ds_read_b128 v[28:31], v185
	s_waitcnt lgkmcnt(0)
	ds_read_b128 v[0:3], v186
	ds_read_b128 v[4:7], v187
	ds_read_b128 v[8:11], v188
	ds_read_b128 v[12:15], v189
	s_add_u32 s36, s34, 0xfff80080
	s_addc_u32 s37, s35, -1
	s_cmp_eq_u32 s60, 28
	s_cselect_b32 s39, s23, s37
	s_cselect_b32 s38, s29, s36
	s_cselect_b32 s37, s21, s59
	s_cselect_b32 s36, s57, s58
	v_lshl_add_u64 v[226:227], s[34:35], 0, v[166:167]
	s_add_i32 m0, s31, 0xc000
	ds_read_b128 v[174:177], v199
	ds_read_b128 v[178:181], v199 offset:1024
	ds_read_b128 v[202:205], v199 offset:2048
	ds_read_b128 v[206:209], v199 offset:3072
	ds_read_b128 v[210:213], v199 offset:4096
	ds_read_b128 v[214:217], v199 offset:5120
	ds_read_b128 v[218:221], v199 offset:6144
	ds_read_b128 v[222:225], v199 offset:7168
	global_load_lds_dwordx4 v[226:227], off
	v_lshl_add_u64 v[226:227], s[34:35], 0, v[168:169]
	s_add_i32 m0, s31, 0xe000
	s_nop 0
	global_load_lds_dwordx4 v[226:227], off
	s_waitcnt vmcnt(8)
	s_waitcnt lgkmcnt(0)
	s_barrier
	s_setprio 1
	s_waitcnt lgkmcnt(0)
	v_mfma_f32_16x16x128_f8f6f4 v[156:159], v[16:23], v[174:181], v[156:159]
	v_mfma_f32_16x16x128_f8f6f4 v[152:155], v[24:31], v[174:181], v[152:155]
	v_mfma_f32_16x16x128_f8f6f4 v[140:143], v[16:23], v[202:209], v[140:143]
	v_mfma_f32_16x16x128_f8f6f4 v[136:139], v[24:31], v[202:209], v[136:139]
	v_mfma_f32_16x16x128_f8f6f4 v[124:127], v[16:23], v[210:217], v[124:127]
	v_mfma_f32_16x16x128_f8f6f4 v[120:123], v[24:31], v[210:217], v[120:123]
	v_mfma_f32_16x16x128_f8f6f4 v[108:111], v[16:23], v[218:225], v[108:111]
	v_mfma_f32_16x16x128_f8f6f4 v[104:107], v[24:31], v[218:225], v[104:107]
	v_mfma_f32_16x16x128_f8f6f4 v[148:151], v[0:7], v[174:181], v[148:151]
	v_mfma_f32_16x16x128_f8f6f4 v[144:147], v[8:15], v[174:181], v[144:147]
	v_mfma_f32_16x16x128_f8f6f4 v[132:135], v[0:7], v[202:209], v[132:135]
	v_mfma_f32_16x16x128_f8f6f4 v[128:131], v[8:15], v[202:209], v[128:131]
	v_mfma_f32_16x16x128_f8f6f4 v[116:119], v[0:7], v[210:217], v[116:119]
	v_mfma_f32_16x16x128_f8f6f4 v[112:115], v[8:15], v[210:217], v[112:115]
	v_mfma_f32_16x16x128_f8f6f4 v[100:103], v[0:7], v[218:225], v[100:103]
	v_mfma_f32_16x16x128_f8f6f4 v[96:99], v[8:15], v[218:225], v[96:99]
	s_setprio 0
	s_barrier
	s_mov_b32 m0, s40
	v_lshl_add_u64 v[174:175], s[36:37], 0, v[160:161]
	s_add_u32 s62, s36, 0x80000
	ds_read_b128 v[202:205], v199 offset:16384
	ds_read_b128 v[206:209], v199 offset:17408
	ds_read_b128 v[210:213], v199 offset:18432
	ds_read_b128 v[214:217], v199 offset:19456
	ds_read_b128 v[218:221], v199 offset:20480
	ds_read_b128 v[222:225], v199 offset:21504
	ds_read_b128 v[226:229], v199 offset:22528
	ds_read_b128 v[230:233], v199 offset:23552
	global_load_lds_dwordx4 v[174:175], off
	v_lshl_add_u64 v[176:177], s[36:37], 0, v[164:165]
	s_mov_b32 m0, s41
	s_addc_u32 s63, s37, 0
	global_load_lds_dwordx4 v[176:177], off
	v_lshl_add_u64 v[178:179], s[62:63], 0, v[160:161]
	s_mov_b32 m0, s42
	v_lshl_add_u64 v[180:181], s[38:39], 0, v[164:165]
	global_load_lds_dwordx4 v[178:179], off
	v_lshl_add_u64 v[178:179], s[62:63], 0, v[164:165]
	s_mov_b32 m0, s43
	s_nop 0
	global_load_lds_dwordx4 v[178:179], off
	v_lshl_add_u64 v[178:179], s[38:39], 0, v[160:161]
	s_mov_b32 m0, s31
	s_nop 0
	global_load_lds_dwordx4 v[178:179], off
	s_mov_b32 m0, s44
	s_nop 0
	global_load_lds_dwordx4 v[180:181], off
	s_waitcnt vmcnt(8)
	s_waitcnt lgkmcnt(0)
	s_barrier
	s_setprio 1
	s_waitcnt lgkmcnt(0)
	v_mfma_f32_16x16x128_f8f6f4 v[92:95], v[16:23], v[202:209], v[92:95]
	v_mfma_f32_16x16x128_f8f6f4 v[88:91], v[24:31], v[202:209], v[88:91]
	v_mfma_f32_16x16x128_f8f6f4 v[76:79], v[16:23], v[210:217], v[76:79]
	v_mfma_f32_16x16x128_f8f6f4 v[72:75], v[24:31], v[210:217], v[72:75]
	v_mfma_f32_16x16x128_f8f6f4 v[60:63], v[16:23], v[218:225], v[60:63]
	v_mfma_f32_16x16x128_f8f6f4 v[56:59], v[24:31], v[218:225], v[56:59]
	v_mfma_f32_16x16x128_f8f6f4 v[44:47], v[16:23], v[226:233], v[44:47]
	v_mfma_f32_16x16x128_f8f6f4 v[40:43], v[24:31], v[226:233], v[40:43]
	v_mfma_f32_16x16x128_f8f6f4 v[84:87], v[0:7], v[202:209], v[84:87]
	v_mfma_f32_16x16x128_f8f6f4 v[80:83], v[8:15], v[202:209], v[80:83]
	v_mfma_f32_16x16x128_f8f6f4 v[68:71], v[0:7], v[210:217], v[68:71]
	v_mfma_f32_16x16x128_f8f6f4 v[64:67], v[8:15], v[210:217], v[64:67]
	v_mfma_f32_16x16x128_f8f6f4 v[52:55], v[0:7], v[218:225], v[52:55]
	v_mfma_f32_16x16x128_f8f6f4 v[48:51], v[8:15], v[218:225], v[48:51]
	v_mfma_f32_16x16x128_f8f6f4 v[36:39], v[0:7], v[226:233], v[36:39]
	v_mfma_f32_16x16x128_f8f6f4 v[32:35], v[8:15], v[226:233], v[32:35]
	s_setprio 0
	s_barrier
; #define PG8_STAGE(bufoff, gbase, voff) do { _Pragma("unroll") for (int _i = 0; _i < 2; ++_i) \
;         __builtin_amdgcn_global_load_lds((const unsigned*)((const char*)(gbase) + (voff)[_i]), (PG8_LAS unsigned*)(lds + (bufoff) + ldsw + _i * 8192), 16, 0, 0); } while (0)
; #define PG8_WAIT_V(n) asm volatile("s_waitcnt vmcnt(" #n ")" ::: "memory")
; #define PG8_WAIT_L(n) asm volatile("s_waitcnt lgkmcnt(" #n ")" ::: "memory")
; #define PG8_BAR __builtin_amdgcn_s_barrier()
; #define PG8_SCHED __builtin_amdgcn_sched_barrier(0)
; template <class Epi, class Sched, bool ALIGN_EPI = false, bool SP2 = false, bool F8 = false>
; __device__ __forceinline__ void gemm_phase(PG8_LAS unsigned char* lds, const Gemm g, const Sched& S, const Epi& E) {
;     ...
;             PG8_LDB(B0, 1, 0); PG8_LDB(B1, 1, 1); PG8_SCHED; PG8_LDA(At, 1, 0); PG8_STAGE(PG8_SA(0, 1), a2 + hstep, voffA);
;             PG8_WAIT_V(8); PG8_WAIT_L(0); PG8_BAR; PG8_MMA(0, 0, At, B0); PG8_MMA(0, 1, At, B1); PG8_BAR; PG8_SCHED;
;             PG8_LDA(At, 1, 1); PG8_STAGE(PG8_SB(1, 0), b3, voffB); PG8_STAGE(PG8_SB(1, 1), b3 + hstep, voffB); PG8_STAGE(PG8_SA(1, 0), a3, voffA);
;             PG8_WAIT_V(8); PG8_WAIT_L(0); PG8_BAR; PG8_MMA(1, 0, At, B0); PG8_MMA(1, 1, At, B1); PG8_BAR; PG8_SCHED;
	ds_read_b128 v[0:3], v190
	ds_read_b128 v[4:7], v191
	ds_read_b128 v[8:11], v192
	ds_read_b128 v[12:15], v193
	ds_read_b128 v[16:19], v194
	ds_read_b128 v[20:23], v195
	ds_read_b128 v[24:27], v196
	ds_read_b128 v[28:31], v197
	s_add_u32 s38, s38, 0x80000
	s_addc_u32 s39, s39, 0
	s_mov_b32 m0, s45
	v_lshl_add_u64 v[234:235], s[38:39], 0, v[160:161]
	ds_read_b128 v[202:205], v199 offset:32768
	ds_read_b128 v[206:209], v199 offset:33792
	ds_read_b128 v[210:213], v199 offset:34816
	ds_read_b128 v[214:217], v199 offset:35840
	ds_read_b128 v[218:221], v199 offset:36864
	ds_read_b128 v[222:225], v199 offset:37888
	ds_read_b128 v[226:229], v199 offset:38912
	ds_read_b128 v[230:233], v199 offset:39936
	global_load_lds_dwordx4 v[234:235], off
	v_lshl_add_u64 v[234:235], s[38:39], 0, v[164:165]
	s_mov_b32 m0, s46
	s_nop 0
	global_load_lds_dwordx4 v[234:235], off
	s_waitcnt vmcnt(8)
	s_waitcnt lgkmcnt(0)
	s_barrier
	s_setprio 1
	s_waitcnt lgkmcnt(0)
	v_mfma_f32_16x16x128_f8f6f4 v[156:159], v[0:7], v[202:209], v[156:159]
	v_mfma_f32_16x16x128_f8f6f4 v[152:155], v[8:15], v[202:209], v[152:155]
	v_mfma_f32_16x16x128_f8f6f4 v[140:143], v[0:7], v[210:217], v[140:143]
	v_mfma_f32_16x16x128_f8f6f4 v[136:139], v[8:15], v[210:217], v[136:139]
	v_mfma_f32_16x16x128_f8f6f4 v[124:127], v[0:7], v[218:225], v[124:127]
	v_mfma_f32_16x16x128_f8f6f4 v[120:123], v[8:15], v[218:225], v[120:123]
	v_mfma_f32_16x16x128_f8f6f4 v[108:111], v[0:7], v[226:233], v[108:111]
	v_mfma_f32_16x16x128_f8f6f4 v[104:107], v[8:15], v[226:233], v[104:107]
	v_mfma_f32_16x16x128_f8f6f4 v[148:151], v[16:23], v[202:209], v[148:151]
	v_mfma_f32_16x16x128_f8f6f4 v[144:147], v[24:31], v[202:209], v[144:147]
	v_mfma_f32_16x16x128_f8f6f4 v[132:135], v[16:23], v[210:217], v[132:135]
	v_mfma_f32_16x16x128_f8f6f4 v[128:131], v[24:31], v[210:217], v[128:131]
	v_mfma_f32_16x16x128_f8f6f4 v[116:119], v[16:23], v[218:225], v[116:119]
	v_mfma_f32_16x16x128_f8f6f4 v[112:115], v[24:31], v[218:225], v[112:115]
	v_mfma_f32_16x16x128_f8f6f4 v[100:103], v[16:23], v[226:233], v[100:103]
	v_mfma_f32_16x16x128_f8f6f4 v[96:99], v[24:31], v[226:233], v[96:99]
	s_setprio 0
	s_barrier
	s_mov_b32 m0, s48
	v_lshl_add_u64 v[174:175], v[174:175], 0, s[14:15]
	s_add_u32 s36, s36, 0x80080
	ds_read_b128 v[202:205], v199 offset:49152
	ds_read_b128 v[206:209], v199 offset:50176
	ds_read_b128 v[210:213], v199 offset:51200
	ds_read_b128 v[214:217], v199 offset:52224
	ds_read_b128 v[218:221], v199 offset:53248
	ds_read_b128 v[222:225], v199 offset:54272
	ds_read_b128 v[226:229], v199 offset:55296
	ds_read_b128 v[230:233], v199 offset:56320
	global_load_lds_dwordx4 v[174:175], off
	v_lshl_add_u64 v[174:175], v[176:177], 0, s[14:15]
	s_mov_b32 m0, s49
	s_addc_u32 s37, s37, 0
	global_load_lds_dwordx4 v[174:175], off
	v_lshl_add_u64 v[174:175], s[36:37], 0, v[160:161]
	s_mov_b32 m0, s52
	s_nop 0
	global_load_lds_dwordx4 v[174:175], off
	v_lshl_add_u64 v[174:175], s[36:37], 0, v[164:165]
	s_mov_b32 m0, s53
	s_nop 0
	global_load_lds_dwordx4 v[174:175], off
	v_lshl_add_u64 v[174:175], v[178:179], 0, s[14:15]
	s_mov_b32 m0, s50
	s_nop 0
	global_load_lds_dwordx4 v[174:175], off
	v_lshl_add_u64 v[174:175], v[180:181], 0, s[14:15]
	s_mov_b32 m0, s51
	s_nop 0
	global_load_lds_dwordx4 v[174:175], off
	s_waitcnt vmcnt(8)
	s_waitcnt lgkmcnt(0)
	s_barrier
	s_setprio 1
	s_waitcnt lgkmcnt(0)
	v_mfma_f32_16x16x128_f8f6f4 v[92:95], v[0:7], v[202:209], v[92:95]
	v_mfma_f32_16x16x128_f8f6f4 v[88:91], v[8:15], v[202:209], v[88:91]
	v_mfma_f32_16x16x128_f8f6f4 v[76:79], v[0:7], v[210:217], v[76:79]
	v_mfma_f32_16x16x128_f8f6f4 v[72:75], v[8:15], v[210:217], v[72:75]
	v_mfma_f32_16x16x128_f8f6f4 v[60:63], v[0:7], v[218:225], v[60:63]
	v_mfma_f32_16x16x128_f8f6f4 v[56:59], v[8:15], v[218:225], v[56:59]
	v_mfma_f32_16x16x128_f8f6f4 v[44:47], v[0:7], v[226:233], v[44:47]
	v_mfma_f32_16x16x128_f8f6f4 v[40:43], v[8:15], v[226:233], v[40:43]
	v_mfma_f32_16x16x128_f8f6f4 v[84:87], v[16:23], v[202:209], v[84:87]
	v_mfma_f32_16x16x128_f8f6f4 v[80:83], v[24:31], v[202:209], v[80:83]
	v_mfma_f32_16x16x128_f8f6f4 v[68:71], v[16:23], v[210:217], v[68:71]
	v_mfma_f32_16x16x128_f8f6f4 v[64:67], v[24:31], v[210:217], v[64:67]
	v_mfma_f32_16x16x128_f8f6f4 v[52:55], v[16:23], v[218:225], v[52:55]
	v_mfma_f32_16x16x128_f8f6f4 v[48:51], v[24:31], v[218:225], v[48:51]
	v_mfma_f32_16x16x128_f8f6f4 v[36:39], v[16:23], v[226:233], v[36:39]
	v_mfma_f32_16x16x128_f8f6f4 v[32:35], v[24:31], v[226:233], v[32:35]
	s_setprio 0
	s_barrier
	s_add_i32 s60, s60, 2
	s_add_u32 s34, s34, 0x100
	s_addc_u32 s35, s35, 0
	s_add_u32 s58, s58, 0x100
	s_addc_u32 s59, s59, 0
	s_cmp_gt_u32 s60, 29
	s_cbranch_scc0 .LBB0_326
	s_and_b64 vcc, exec, s[16:17]
	s_cbranch_vccz .LBB0_329
	s_barrier

; #define PG8_STAGE(bufoff, gbase, voff) do { _Pragma("unroll") for (int _i = 0; _i < 2; ++_i) \
;         __builtin_amdgcn_global_load_lds((const unsigned*)((const char*)(gbase) + (voff)[_i]), (PG8_LAS unsigned*)(lds + (bufoff) + ldsw + _i * 8192), 16, 0, 0); } while (0)
; #define PG8_WAIT_V(n) asm volatile("s_waitcnt vmcnt(" #n ")" ::: "memory")
; #define PG8_WAIT_L(n) asm volatile("s_waitcnt lgkmcnt(" #n ")" ::: "memory")
; #define PG8_BAR __builtin_amdgcn_s_barrier()
; #define PG8_SCHED __builtin_amdgcn_sched_barrier(0)
; template <class Epi, class Sched, bool ALIGN_EPI = false, bool SP2 = false, bool F8 = false>
; __device__ __forceinline__ void gemm_phase(PG8_LAS unsigned char* lds, const Gemm g, const Sched& S, const Epi& E) {
;     ...
;             PG8_LDB(B0, 0, 0); PG8_LDB(B1, 0, 1); PG8_SCHED; PG8_LDA(At, 0, 0); PG8_STAGE(PG8_SA(1, 1), a1 + hstep, voffA);
;             PG8_WAIT_V(8); PG8_WAIT_L(0); PG8_BAR; PG8_MMA(0, 0, At, B0); PG8_MMA(0, 1, At, B1); PG8_BAR; PG8_SCHED;
;             PG8_LDA(At, 0, 1); PG8_STAGE(PG8_SB(0, 0), b2, voffB); PG8_STAGE(PG8_SB(0, 1), b2 + hstep, voffB); PG8_STAGE(PG8_SA(0, 0), a2, voffA);
;             PG8_WAIT_V(8); PG8_WAIT_L(0); PG8_BAR; PG8_MMA(1, 0, At, B0); PG8_MMA(1, 1, At, B1); PG8_BAR; PG8_SCHED;
.LBB0_419:
	ds_read_b128 v[128:131], v169
	ds_read_b128 v[132:135], v169 offset:1024
	ds_read_b128 v[158:161], v169 offset:2048
	ds_read_b128 v[164:167], v169 offset:3072
	ds_read_b128 v[174:177], v170
	ds_read_b128 v[178:181], v170 offset:1024
	ds_read_b128 v[182:185], v170 offset:2048
	ds_read_b128 v[186:189], v170 offset:3072
	s_add_u32 s30, s28, 0xfff00080
	s_addc_u32 s31, s29, -1
	s_cmp_eq_u32 s54, 60
	s_cselect_b32 s35, s5, s31
	s_cselect_b32 s34, s7, s30
	s_cselect_b32 s31, s21, s53
	s_cselect_b32 s30, s23, s52
	v_lshl_add_u64 v[136:137], s[28:29], 0, v[150:151]
	s_add_i32 m0, s38, 0xc000
	ds_read_b128 v[190:193], v171
	ds_read_b128 v[194:197], v171 offset:1024
	ds_read_b128 v[198:201], v171 offset:2048
	ds_read_b128 v[202:205], v171 offset:3072
	ds_read_b128 v[206:209], v171 offset:4096
	ds_read_b128 v[210:213], v171 offset:5120
	ds_read_b128 v[214:217], v171 offset:6144
	ds_read_b128 v[218:221], v171 offset:7168
	global_load_lds_dwordx4 v[136:137], off
	v_lshl_add_u64 v[136:137], s[28:29], 0, v[152:153]
	s_add_i32 m0, s38, 0xe000
	s_nop 0
	global_load_lds_dwordx4 v[136:137], off
	s_waitcnt vmcnt(8)
	s_waitcnt lgkmcnt(0)
	s_barrier
	s_setprio 1
	s_waitcnt lgkmcnt(0)
	v_mfma_f32_16x16x32_bf16 v[124:127], v[128:131], v[190:193], v[124:127]
	v_mfma_f32_16x16x32_bf16 v[120:123], v[158:161], v[190:193], v[120:123]
	v_mfma_f32_16x16x32_bf16 v[108:111], v[128:131], v[198:201], v[108:111]
	v_mfma_f32_16x16x32_bf16 v[104:107], v[158:161], v[198:201], v[104:107]
	v_mfma_f32_16x16x32_bf16 v[92:95], v[128:131], v[206:209], v[92:95]
	v_mfma_f32_16x16x32_bf16 v[88:91], v[158:161], v[206:209], v[88:91]
	v_mfma_f32_16x16x32_bf16 v[76:79], v[128:131], v[214:217], v[76:79]
	v_mfma_f32_16x16x32_bf16 v[72:75], v[158:161], v[214:217], v[72:75]
	v_mfma_f32_16x16x32_bf16 v[124:127], v[132:135], v[194:197], v[124:127]
	v_mfma_f32_16x16x32_bf16 v[120:123], v[164:167], v[194:197], v[120:123]
	v_mfma_f32_16x16x32_bf16 v[108:111], v[132:135], v[202:205], v[108:111]
	v_mfma_f32_16x16x32_bf16 v[104:107], v[164:167], v[202:205], v[104:107]
	v_mfma_f32_16x16x32_bf16 v[92:95], v[132:135], v[210:213], v[92:95]
	v_mfma_f32_16x16x32_bf16 v[88:91], v[164:167], v[210:213], v[88:91]
	v_mfma_f32_16x16x32_bf16 v[76:79], v[132:135], v[218:221], v[76:79]
	v_mfma_f32_16x16x32_bf16 v[72:75], v[164:167], v[218:221], v[72:75]
	v_mfma_f32_16x16x32_bf16 v[116:119], v[174:177], v[190:193], v[116:119]
	v_mfma_f32_16x16x32_bf16 v[112:115], v[182:185], v[190:193], v[112:115]
	v_mfma_f32_16x16x32_bf16 v[100:103], v[174:177], v[198:201], v[100:103]
	v_mfma_f32_16x16x32_bf16 v[96:99], v[182:185], v[198:201], v[96:99]
	v_mfma_f32_16x16x32_bf16 v[84:87], v[174:177], v[206:209], v[84:87]
	v_mfma_f32_16x16x32_bf16 v[80:83], v[182:185], v[206:209], v[80:83]
	v_mfma_f32_16x16x32_bf16 v[68:71], v[174:177], v[214:217], v[68:71]
	v_mfma_f32_16x16x32_bf16 v[64:67], v[182:185], v[214:217], v[64:67]
	v_mfma_f32_16x16x32_bf16 v[116:119], v[178:181], v[194:197], v[116:119]
	v_mfma_f32_16x16x32_bf16 v[112:115], v[186:189], v[194:197], v[112:115]
	v_mfma_f32_16x16x32_bf16 v[100:103], v[178:181], v[202:205], v[100:103]
	v_mfma_f32_16x16x32_bf16 v[96:99], v[186:189], v[202:205], v[96:99]
	v_mfma_f32_16x16x32_bf16 v[84:87], v[178:181], v[210:213], v[84:87]
	v_mfma_f32_16x16x32_bf16 v[80:83], v[186:189], v[210:213], v[80:83]
	v_mfma_f32_16x16x32_bf16 v[68:71], v[178:181], v[218:221], v[68:71]
	v_mfma_f32_16x16x32_bf16 v[64:67], v[186:189], v[218:221], v[64:67]
	s_setprio 0
	s_barrier
	s_add_i32 s55, s49, s37
	v_lshl_add_u64 v[136:137], s[30:31], 0, v[140:141]
	s_mov_b32 m0, s55
	ds_read_b128 v[190:193], v171 offset:16384
	ds_read_b128 v[194:197], v171 offset:17408
	ds_read_b128 v[198:201], v171 offset:18432
	ds_read_b128 v[202:205], v171 offset:19456
	ds_read_b128 v[206:209], v171 offset:20480
	ds_read_b128 v[210:213], v171 offset:21504
	ds_read_b128 v[214:217], v171 offset:22528
	ds_read_b128 v[218:221], v171 offset:23552
	global_load_lds_dwordx4 v[136:137], off
	s_add_i32 m0, s55, 0x2000
	s_add_u32 s56, s30, 0x100000
	v_lshl_add_u64 v[222:223], s[30:31], 0, v[144:145]
	s_addc_u32 s57, s31, 0
	s_add_i32 s55, s50, s37
	global_load_lds_dwordx4 v[222:223], off
	v_lshl_add_u64 v[224:225], s[56:57], 0, v[140:141]
	s_mov_b32 m0, s55
	v_lshl_add_u64 v[226:227], s[34:35], 0, v[142:143]
	global_load_lds_dwordx4 v[224:225], off
	v_lshl_add_u64 v[224:225], s[56:57], 0, v[144:145]
	s_add_i32 m0, s55, 0x2000
	s_nop 0
	global_load_lds_dwordx4 v[224:225], off
	v_lshl_add_u64 v[224:225], s[34:35], 0, v[138:139]
	s_mov_b32 m0, s38
	s_nop 0
	global_load_lds_dwordx4 v[224:225], off
	s_mov_b32 m0, s39
	s_nop 0
	global_load_lds_dwordx4 v[226:227], off
	s_waitcnt vmcnt(8)
	s_waitcnt lgkmcnt(0)
	s_barrier
; #define PG8_STAGE(bufoff, gbase, voff) do { _Pragma("unroll") for (int _i = 0; _i < 2; ++_i) \
;         __builtin_amdgcn_global_load_lds((const unsigned*)((const char*)(gbase) + (voff)[_i]), (PG8_LAS unsigned*)(lds + (bufoff) + ldsw + _i * 8192), 16, 0, 0); } while (0)
; #define PG8_WAIT_V(n) asm volatile("s_waitcnt vmcnt(" #n ")" ::: "memory")
; #define PG8_WAIT_L(n) asm volatile("s_waitcnt lgkmcnt(" #n ")" ::: "memory")
; #define PG8_BAR __builtin_amdgcn_s_barrier()
; #define PG8_SCHED __builtin_amdgcn_sched_barrier(0)
; template <class Epi, class Sched, bool ALIGN_EPI = false, bool SP2 = false, bool F8 = false>
; __device__ __forceinline__ void gemm_phase(PG8_LAS unsigned char* lds, const Gemm g, const Sched& S, const Epi& E) {
;     ...
;             PG8_WAIT_V(8); PG8_WAIT_L(0); PG8_BAR; PG8_MMA(1, 0, At, B0); PG8_MMA(1, 1, At, B1); PG8_BAR; PG8_SCHED;
;             PG8_LDB(B0, 1, 0); PG8_LDB(B1, 1, 1); PG8_SCHED; PG8_LDA(At, 1, 0); PG8_STAGE(PG8_SA(0, 1), a2 + hstep, voffA);
;             PG8_WAIT_V(8); PG8_WAIT_L(0); PG8_BAR; PG8_MMA(0, 0, At, B0); PG8_MMA(0, 1, At, B1); PG8_BAR; PG8_SCHED;
	s_setprio 1
	s_waitcnt lgkmcnt(0)
	v_mfma_f32_16x16x32_bf16 v[60:63], v[128:131], v[190:193], v[60:63]
	v_mfma_f32_16x16x32_bf16 v[56:59], v[158:161], v[190:193], v[56:59]
	v_mfma_f32_16x16x32_bf16 v[44:47], v[128:131], v[198:201], v[44:47]
	v_mfma_f32_16x16x32_bf16 v[40:43], v[158:161], v[198:201], v[40:43]
	v_mfma_f32_16x16x32_bf16 v[28:31], v[128:131], v[206:209], v[28:31]
	v_mfma_f32_16x16x32_bf16 v[24:27], v[158:161], v[206:209], v[24:27]
	v_mfma_f32_16x16x32_bf16 v[12:15], v[128:131], v[214:217], v[12:15]
	v_mfma_f32_16x16x32_bf16 v[8:11], v[158:161], v[214:217], v[8:11]
	v_mfma_f32_16x16x32_bf16 v[60:63], v[132:135], v[194:197], v[60:63]
	v_mfma_f32_16x16x32_bf16 v[56:59], v[164:167], v[194:197], v[56:59]
	v_mfma_f32_16x16x32_bf16 v[44:47], v[132:135], v[202:205], v[44:47]
	v_mfma_f32_16x16x32_bf16 v[40:43], v[164:167], v[202:205], v[40:43]
	v_mfma_f32_16x16x32_bf16 v[28:31], v[132:135], v[210:213], v[28:31]
	v_mfma_f32_16x16x32_bf16 v[24:27], v[164:167], v[210:213], v[24:27]
	v_mfma_f32_16x16x32_bf16 v[12:15], v[132:135], v[218:221], v[12:15]
	v_mfma_f32_16x16x32_bf16 v[8:11], v[164:167], v[218:221], v[8:11]
	v_mfma_f32_16x16x32_bf16 v[52:55], v[174:177], v[190:193], v[52:55]
	v_mfma_f32_16x16x32_bf16 v[48:51], v[182:185], v[190:193], v[48:51]
	v_mfma_f32_16x16x32_bf16 v[36:39], v[174:177], v[198:201], v[36:39]
	v_mfma_f32_16x16x32_bf16 v[32:35], v[182:185], v[198:201], v[32:35]
	v_mfma_f32_16x16x32_bf16 v[20:23], v[174:177], v[206:209], v[20:23]
	v_mfma_f32_16x16x32_bf16 v[16:19], v[182:185], v[206:209], v[16:19]
	v_mfma_f32_16x16x32_bf16 v[4:7], v[174:177], v[214:217], v[4:7]
	v_mfma_f32_16x16x32_bf16 v[0:3], v[182:185], v[214:217], v[0:3]
	v_mfma_f32_16x16x32_bf16 v[52:55], v[178:181], v[194:197], v[52:55]
	v_mfma_f32_16x16x32_bf16 v[48:51], v[186:189], v[194:197], v[48:51]
	v_mfma_f32_16x16x32_bf16 v[36:39], v[178:181], v[202:205], v[36:39]
	v_mfma_f32_16x16x32_bf16 v[32:35], v[186:189], v[202:205], v[32:35]
	v_mfma_f32_16x16x32_bf16 v[20:23], v[178:181], v[210:213], v[20:23]
	v_mfma_f32_16x16x32_bf16 v[16:19], v[186:189], v[210:213], v[16:19]
	v_mfma_f32_16x16x32_bf16 v[4:7], v[178:181], v[218:221], v[4:7]
	v_mfma_f32_16x16x32_bf16 v[0:3], v[186:189], v[218:221], v[0:3]
	s_setprio 0
	s_barrier
	s_add_i32 s55, 0, 0x18000
	s_add_i32 s56, 0, 0x1c000
	v_add_u32_e32 v164, s55, v168
	v_add_u32_e32 v173, s56, v168
	ds_read_b128 v[128:131], v164
	ds_read_b128 v[132:135], v164 offset:1024
	ds_read_b128 v[158:161], v164 offset:2048
	ds_read_b128 v[164:167], v164 offset:3072
	ds_read_b128 v[174:177], v173
	ds_read_b128 v[178:181], v173 offset:1024
	ds_read_b128 v[182:185], v173 offset:2048
	ds_read_b128 v[186:189], v173 offset:3072
	s_add_u32 s34, s34, 0x100000
	s_addc_u32 s35, s35, 0
	s_mov_b32 m0, s40
	v_lshl_add_u64 v[228:229], s[34:35], 0, v[138:139]
	ds_read_b128 v[190:193], v171 offset:32768
	ds_read_b128 v[194:197], v171 offset:33792
	ds_read_b128 v[198:201], v171 offset:34816
	ds_read_b128 v[202:205], v171 offset:35840
	ds_read_b128 v[206:209], v171 offset:36864
	ds_read_b128 v[210:213], v171 offset:37888
	ds_read_b128 v[214:217], v171 offset:38912
	ds_read_b128 v[218:221], v171 offset:39936
	global_load_lds_dwordx4 v[228:229], off
	v_lshl_add_u64 v[228:229], s[34:35], 0, v[142:143]
	s_mov_b32 m0, s41
	s_nop 0
	global_load_lds_dwordx4 v[228:229], off
	s_waitcnt vmcnt(8)
	s_waitcnt lgkmcnt(0)
	s_barrier
	s_setprio 1
	s_waitcnt lgkmcnt(0)
	v_mfma_f32_16x16x32_bf16 v[124:127], v[128:131], v[190:193], v[124:127]
	v_mfma_f32_16x16x32_bf16 v[120:123], v[158:161], v[190:193], v[120:123]
	v_mfma_f32_16x16x32_bf16 v[108:111], v[128:131], v[198:201], v[108:111]
	v_mfma_f32_16x16x32_bf16 v[104:107], v[158:161], v[198:201], v[104:107]
	v_mfma_f32_16x16x32_bf16 v[92:95], v[128:131], v[206:209], v[92:95]
	v_mfma_f32_16x16x32_bf16 v[88:91], v[158:161], v[206:209], v[88:91]
	v_mfma_f32_16x16x32_bf16 v[76:79], v[128:131], v[214:217], v[76:79]
	v_mfma_f32_16x16x32_bf16 v[72:75], v[158:161], v[214:217], v[72:75]
	v_mfma_f32_16x16x32_bf16 v[124:127], v[132:135], v[194:197], v[124:127]
	v_mfma_f32_16x16x32_bf16 v[120:123], v[164:167], v[194:197], v[120:123]
	v_mfma_f32_16x16x32_bf16 v[108:111], v[132:135], v[202:205], v[108:111]
	v_mfma_f32_16x16x32_bf16 v[104:107], v[164:167], v[202:205], v[104:107]
	v_mfma_f32_16x16x32_bf16 v[92:95], v[132:135], v[210:213], v[92:95]
	v_mfma_f32_16x16x32_bf16 v[88:91], v[164:167], v[210:213], v[88:91]
	v_mfma_f32_16x16x32_bf16 v[76:79], v[132:135], v[218:221], v[76:79]
	v_mfma_f32_16x16x32_bf16 v[72:75], v[164:167], v[218:221], v[72:75]
	v_mfma_f32_16x16x32_bf16 v[116:119], v[174:177], v[190:193], v[116:119]
	v_mfma_f32_16x16x32_bf16 v[112:115], v[182:185], v[190:193], v[112:115]
	v_mfma_f32_16x16x32_bf16 v[100:103], v[174:177], v[198:201], v[100:103]
	v_mfma_f32_16x16x32_bf16 v[96:99], v[182:185], v[198:201], v[96:99]
	v_mfma_f32_16x16x32_bf16 v[84:87], v[174:177], v[206:209], v[84:87]
	v_mfma_f32_16x16x32_bf16 v[80:83], v[182:185], v[206:209], v[80:83]
	v_mfma_f32_16x16x32_bf16 v[68:71], v[174:177], v[214:217], v[68:71]
	v_mfma_f32_16x16x32_bf16 v[64:67], v[182:185], v[214:217], v[64:67]
	v_mfma_f32_16x16x32_bf16 v[116:119], v[178:181], v[194:197], v[116:119]
	v_mfma_f32_16x16x32_bf16 v[112:115], v[186:189], v[194:197], v[112:115]
	v_mfma_f32_16x16x32_bf16 v[100:103], v[178:181], v[202:205], v[100:103]
	v_mfma_f32_16x16x32_bf16 v[96:99], v[186:189], v[202:205], v[96:99]
	v_mfma_f32_16x16x32_bf16 v[84:87], v[178:181], v[210:213], v[84:87]
	v_mfma_f32_16x16x32_bf16 v[80:83], v[186:189], v[210:213], v[80:83]
	v_mfma_f32_16x16x32_bf16 v[68:71], v[178:181], v[218:221], v[68:71]
	v_mfma_f32_16x16x32_bf16 v[64:67], v[186:189], v[218:221], v[64:67]
	s_setprio 0
	s_barrier
; #define PG8_STAGE(bufoff, gbase, voff) do { _Pragma("unroll") for (int _i = 0; _i < 2; ++_i) \
;         __builtin_amdgcn_global_load_lds((const unsigned*)((const char*)(gbase) + (voff)[_i]), (PG8_LAS unsigned*)(lds + (bufoff) + ldsw + _i * 8192), 16, 0, 0); } while (0)
; #define PG8_WAIT_V(n) asm volatile("s_waitcnt vmcnt(" #n ")" ::: "memory")
; #define PG8_WAIT_L(n) asm volatile("s_waitcnt lgkmcnt(" #n ")" ::: "memory")
; #define PG8_BAR __builtin_amdgcn_s_barrier()
; #define PG8_SCHED __builtin_amdgcn_sched_barrier(0)
; template <class Epi, class Sched, bool ALIGN_EPI = false, bool SP2 = false, bool F8 = false>
; __device__ __forceinline__ void gemm_phase(PG8_LAS unsigned char* lds, const Gemm g, const Sched& S, const Epi& E) {
;     ...
;             PG8_LDA(At, 1, 1); PG8_STAGE(PG8_SB(1, 0), b3, voffB); PG8_STAGE(PG8_SB(1, 1), b3 + hstep, voffB); PG8_STAGE(PG8_SA(1, 0), a3, voffA);
;             PG8_WAIT_V(8); PG8_WAIT_L(0); PG8_BAR; PG8_MMA(1, 0, At, B0); PG8_MMA(1, 1, At, B1); PG8_BAR; PG8_SCHED;
	s_add_i32 s34, s55, s37
	v_lshl_add_u64 v[136:137], v[136:137], 0, s[16:17]
	s_mov_b32 m0, s34
	ds_read_b128 v[190:193], v171 offset:49152
	ds_read_b128 v[194:197], v171 offset:50176
	ds_read_b128 v[198:201], v171 offset:51200
	ds_read_b128 v[202:205], v171 offset:52224
	ds_read_b128 v[206:209], v171 offset:53248
	ds_read_b128 v[210:213], v171 offset:54272
	ds_read_b128 v[214:217], v171 offset:55296
	ds_read_b128 v[218:221], v171 offset:56320
	global_load_lds_dwordx4 v[136:137], off
	s_add_i32 m0, s34, 0x2000
	s_add_u32 s30, s30, 0x100080
	v_lshl_add_u64 v[136:137], v[222:223], 0, s[16:17]
	s_addc_u32 s31, s31, 0
	s_add_i32 s34, s56, s37
	global_load_lds_dwordx4 v[136:137], off
	v_lshl_add_u64 v[136:137], s[30:31], 0, v[140:141]
	s_mov_b32 m0, s34
	s_nop 0
	global_load_lds_dwordx4 v[136:137], off
	v_lshl_add_u64 v[136:137], s[30:31], 0, v[144:145]
	s_add_i32 m0, s34, 0x2000
	s_nop 0
	global_load_lds_dwordx4 v[136:137], off
	v_lshl_add_u64 v[136:137], v[224:225], 0, s[16:17]
	s_mov_b32 m0, s44
	s_nop 0
	global_load_lds_dwordx4 v[136:137], off
	v_lshl_add_u64 v[136:137], v[226:227], 0, s[16:17]
	s_mov_b32 m0, s45
	s_nop 0
	global_load_lds_dwordx4 v[136:137], off
	s_waitcnt vmcnt(8)
	s_waitcnt lgkmcnt(0)
	s_barrier
	s_setprio 1
	s_waitcnt lgkmcnt(0)
	v_mfma_f32_16x16x32_bf16 v[60:63], v[128:131], v[190:193], v[60:63]
	v_mfma_f32_16x16x32_bf16 v[56:59], v[158:161], v[190:193], v[56:59]
	v_mfma_f32_16x16x32_bf16 v[44:47], v[128:131], v[198:201], v[44:47]
	v_mfma_f32_16x16x32_bf16 v[40:43], v[158:161], v[198:201], v[40:43]
	v_mfma_f32_16x16x32_bf16 v[28:31], v[128:131], v[206:209], v[28:31]
	v_mfma_f32_16x16x32_bf16 v[24:27], v[158:161], v[206:209], v[24:27]
	v_mfma_f32_16x16x32_bf16 v[12:15], v[128:131], v[214:217], v[12:15]
	v_mfma_f32_16x16x32_bf16 v[8:11], v[158:161], v[214:217], v[8:11]
	v_mfma_f32_16x16x32_bf16 v[60:63], v[132:135], v[194:197], v[60:63]
	v_mfma_f32_16x16x32_bf16 v[56:59], v[164:167], v[194:197], v[56:59]
	v_mfma_f32_16x16x32_bf16 v[44:47], v[132:135], v[202:205], v[44:47]
	v_mfma_f32_16x16x32_bf16 v[40:43], v[164:167], v[202:205], v[40:43]
	v_mfma_f32_16x16x32_bf16 v[28:31], v[132:135], v[210:213], v[28:31]
	v_mfma_f32_16x16x32_bf16 v[24:27], v[164:167], v[210:213], v[24:27]
	v_mfma_f32_16x16x32_bf16 v[12:15], v[132:135], v[218:221], v[12:15]
	v_mfma_f32_16x16x32_bf16 v[8:11], v[164:167], v[218:221], v[8:11]
	v_mfma_f32_16x16x32_bf16 v[52:55], v[174:177], v[190:193], v[52:55]
	v_mfma_f32_16x16x32_bf16 v[48:51], v[182:185], v[190:193], v[48:51]
	v_mfma_f32_16x16x32_bf16 v[36:39], v[174:177], v[198:201], v[36:39]
	v_mfma_f32_16x16x32_bf16 v[32:35], v[182:185], v[198:201], v[32:35]
	v_mfma_f32_16x16x32_bf16 v[20:23], v[174:177], v[206:209], v[20:23]
	v_mfma_f32_16x16x32_bf16 v[16:19], v[182:185], v[206:209], v[16:19]
	v_mfma_f32_16x16x32_bf16 v[4:7], v[174:177], v[214:217], v[4:7]
	v_mfma_f32_16x16x32_bf16 v[0:3], v[182:185], v[214:217], v[0:3]
	v_mfma_f32_16x16x32_bf16 v[52:55], v[178:181], v[194:197], v[52:55]
	v_mfma_f32_16x16x32_bf16 v[48:51], v[186:189], v[194:197], v[48:51]
	v_mfma_f32_16x16x32_bf16 v[36:39], v[178:181], v[202:205], v[36:39]
	v_mfma_f32_16x16x32_bf16 v[32:35], v[186:189], v[202:205], v[32:35]
	v_mfma_f32_16x16x32_bf16 v[20:23], v[178:181], v[210:213], v[20:23]
	v_mfma_f32_16x16x32_bf16 v[16:19], v[186:189], v[210:213], v[16:19]
	v_mfma_f32_16x16x32_bf16 v[4:7], v[178:181], v[218:221], v[4:7]
	v_mfma_f32_16x16x32_bf16 v[0:3], v[186:189], v[218:221], v[0:3]
	s_setprio 0
	s_barrier
	s_add_i32 s54, s54, 2
	s_add_u32 s28, s28, 0x100
	s_addc_u32 s29, s29, 0
	s_add_u32 s52, s52, 0x100
	s_addc_u32 s53, s53, 0
	s_cmp_gt_u32 s54, 61
	s_cbranch_scc0 .LBB0_419
	s_and_b64 vcc, exec, s[18:19]
	s_cbranch_vccz .LBB0_422
	s_barrier

; #define PG8_STAGE(bufoff, gbase, voff) do { _Pragma("unroll") for (int _i = 0; _i < 2; ++_i) \
;         __builtin_amdgcn_global_load_lds((const unsigned*)((const char*)(gbase) + (voff)[_i]), (PG8_LAS unsigned*)(lds + (bufoff) + ldsw + _i * 8192), 16, 0, 0); } while (0)
; #define PG8_WAIT_V(n) asm volatile("s_waitcnt vmcnt(" #n ")" ::: "memory")
; #define PG8_WAIT_L(n) asm volatile("s_waitcnt lgkmcnt(" #n ")" ::: "memory")
; #define PG8_BAR __builtin_amdgcn_s_barrier()
; #define PG8_SCHED __builtin_amdgcn_sched_barrier(0)
; template <class Epi, class Sched, bool ALIGN_EPI = false, bool SP2 = false, bool F8 = false>
; __device__ __forceinline__ void gemm_phase(PG8_LAS unsigned char* lds, const Gemm g, const Sched& S, const Epi& E) {
;     ...
;             PG8_LDB(B0, 0, 0); PG8_LDB(B1, 0, 1); PG8_SCHED; PG8_LDA(At, 0, 0); PG8_STAGE(PG8_SA(1, 1), a1 + hstep, voffA);
;             PG8_WAIT_V(8); PG8_WAIT_L(0); PG8_BAR; PG8_MMA(0, 0, At, B0); PG8_MMA(0, 1, At, B1); PG8_BAR; PG8_SCHED;
;             PG8_LDA(At, 0, 1); PG8_STAGE(PG8_SB(0, 0), b2, voffB); PG8_STAGE(PG8_SB(0, 1), b2 + hstep, voffB); PG8_STAGE(PG8_SA(0, 0), a2, voffA);
;             PG8_WAIT_V(8); PG8_WAIT_L(0); PG8_BAR; PG8_MMA(1, 0, At, B0); PG8_MMA(1, 1, At, B1); PG8_BAR; PG8_SCHED;
.LBB0_644:
	ds_read_b128 v[140:143], v148
	ds_read_b128 v[152:155], v148 offset:1024
	ds_read_b128 v[156:159], v148 offset:2048
	ds_read_b128 v[164:167], v148 offset:3072
	ds_read_b128 v[168:171], v149
	ds_read_b128 v[172:175], v149 offset:1024
	ds_read_b128 v[176:179], v149 offset:2048
	ds_read_b128 v[180:183], v149 offset:3072
	s_add_u32 s36, s34, 0xfff00080
	s_addc_u32 s37, s35, -1
	s_cmp_eq_u32 s56, 60
	s_cselect_b32 s39, s23, s37
	s_cselect_b32 s38, s29, s36
	s_cselect_b32 s37, s21, s55
	s_cselect_b32 s36, s53, s54
	v_lshl_add_u64 v[160:161], s[34:35], 0, v[132:133]
	s_add_i32 m0, s31, 0xc000
	ds_read_b128 v[184:187], v150
	ds_read_b128 v[188:191], v150 offset:1024
	ds_read_b128 v[192:195], v150 offset:2048
	ds_read_b128 v[196:199], v150 offset:3072
	ds_read_b128 v[200:203], v150 offset:4096
	ds_read_b128 v[204:207], v150 offset:5120
	ds_read_b128 v[208:211], v150 offset:6144
	ds_read_b128 v[212:215], v150 offset:7168
	global_load_lds_dwordx4 v[160:161], off
	v_lshl_add_u64 v[160:161], s[34:35], 0, v[134:135]
	s_add_i32 m0, s31, 0xe000
	s_nop 0
	global_load_lds_dwordx4 v[160:161], off
	s_waitcnt vmcnt(8)
	s_waitcnt lgkmcnt(0)
	s_barrier
	s_setprio 1
	s_waitcnt lgkmcnt(0)
	v_mfma_f32_16x16x32_bf16 v[124:127], v[140:143], v[184:187], v[124:127]
	v_mfma_f32_16x16x32_bf16 v[120:123], v[156:159], v[184:187], v[120:123]
	v_mfma_f32_16x16x32_bf16 v[108:111], v[140:143], v[192:195], v[108:111]
	v_mfma_f32_16x16x32_bf16 v[104:107], v[156:159], v[192:195], v[104:107]
	v_mfma_f32_16x16x32_bf16 v[92:95], v[140:143], v[200:203], v[92:95]
	v_mfma_f32_16x16x32_bf16 v[88:91], v[156:159], v[200:203], v[88:91]
	v_mfma_f32_16x16x32_bf16 v[76:79], v[140:143], v[208:211], v[76:79]
	v_mfma_f32_16x16x32_bf16 v[72:75], v[156:159], v[208:211], v[72:75]
	v_mfma_f32_16x16x32_bf16 v[124:127], v[152:155], v[188:191], v[124:127]
	v_mfma_f32_16x16x32_bf16 v[120:123], v[164:167], v[188:191], v[120:123]
	v_mfma_f32_16x16x32_bf16 v[108:111], v[152:155], v[196:199], v[108:111]
	v_mfma_f32_16x16x32_bf16 v[104:107], v[164:167], v[196:199], v[104:107]
	v_mfma_f32_16x16x32_bf16 v[92:95], v[152:155], v[204:207], v[92:95]
	v_mfma_f32_16x16x32_bf16 v[88:91], v[164:167], v[204:207], v[88:91]
	v_mfma_f32_16x16x32_bf16 v[76:79], v[152:155], v[212:215], v[76:79]
	v_mfma_f32_16x16x32_bf16 v[72:75], v[164:167], v[212:215], v[72:75]
	v_mfma_f32_16x16x32_bf16 v[116:119], v[168:171], v[184:187], v[116:119]
	v_mfma_f32_16x16x32_bf16 v[112:115], v[176:179], v[184:187], v[112:115]
	v_mfma_f32_16x16x32_bf16 v[100:103], v[168:171], v[192:195], v[100:103]
	v_mfma_f32_16x16x32_bf16 v[96:99], v[176:179], v[192:195], v[96:99]
	v_mfma_f32_16x16x32_bf16 v[84:87], v[168:171], v[200:203], v[84:87]
	v_mfma_f32_16x16x32_bf16 v[80:83], v[176:179], v[200:203], v[80:83]
	v_mfma_f32_16x16x32_bf16 v[68:71], v[168:171], v[208:211], v[68:71]
	v_mfma_f32_16x16x32_bf16 v[64:67], v[176:179], v[208:211], v[64:67]
	v_mfma_f32_16x16x32_bf16 v[116:119], v[172:175], v[188:191], v[116:119]
	v_mfma_f32_16x16x32_bf16 v[112:115], v[180:183], v[188:191], v[112:115]
	v_mfma_f32_16x16x32_bf16 v[100:103], v[172:175], v[196:199], v[100:103]
	v_mfma_f32_16x16x32_bf16 v[96:99], v[180:183], v[196:199], v[96:99]
	v_mfma_f32_16x16x32_bf16 v[84:87], v[172:175], v[204:207], v[84:87]
	v_mfma_f32_16x16x32_bf16 v[80:83], v[180:183], v[204:207], v[80:83]
	v_mfma_f32_16x16x32_bf16 v[68:71], v[172:175], v[212:215], v[68:71]
	v_mfma_f32_16x16x32_bf16 v[64:67], v[180:183], v[212:215], v[64:67]
	s_setprio 0
	s_barrier
	s_add_i32 s57, s51, s41
	v_lshl_add_u64 v[160:161], s[36:37], 0, v[128:129]
	s_mov_b32 m0, s57
	ds_read_b128 v[184:187], v150 offset:16384
	ds_read_b128 v[188:191], v150 offset:17408
	ds_read_b128 v[192:195], v150 offset:18432
	ds_read_b128 v[196:199], v150 offset:19456
	ds_read_b128 v[200:203], v150 offset:20480
	ds_read_b128 v[204:207], v150 offset:21504
	ds_read_b128 v[208:211], v150 offset:22528
	ds_read_b128 v[212:215], v150 offset:23552
	global_load_lds_dwordx4 v[160:161], off
	s_add_i32 m0, s57, 0x2000
	s_add_u32 s58, s36, 0x100000
	v_lshl_add_u64 v[216:217], s[36:37], 0, v[130:131]
	s_addc_u32 s59, s37, 0
	s_add_i32 s57, s52, s41
	global_load_lds_dwordx4 v[216:217], off
	v_lshl_add_u64 v[218:219], s[58:59], 0, v[128:129]
	s_mov_b32 m0, s57
	v_lshl_add_u64 v[220:221], s[38:39], 0, v[130:131]
	global_load_lds_dwordx4 v[218:219], off
	v_lshl_add_u64 v[218:219], s[58:59], 0, v[130:131]
	s_add_i32 m0, s57, 0x2000
	s_nop 0
	global_load_lds_dwordx4 v[218:219], off
	v_lshl_add_u64 v[218:219], s[38:39], 0, v[128:129]
	s_mov_b32 m0, s31
	s_nop 0
	global_load_lds_dwordx4 v[218:219], off
	s_mov_b32 m0, s42
	s_nop 0
	global_load_lds_dwordx4 v[220:221], off
	s_waitcnt vmcnt(8)
	s_waitcnt lgkmcnt(0)
	s_barrier
; #define PG8_STAGE(bufoff, gbase, voff) do { _Pragma("unroll") for (int _i = 0; _i < 2; ++_i) \
;         __builtin_amdgcn_global_load_lds((const unsigned*)((const char*)(gbase) + (voff)[_i]), (PG8_LAS unsigned*)(lds + (bufoff) + ldsw + _i * 8192), 16, 0, 0); } while (0)
; #define PG8_WAIT_V(n) asm volatile("s_waitcnt vmcnt(" #n ")" ::: "memory")
; #define PG8_WAIT_L(n) asm volatile("s_waitcnt lgkmcnt(" #n ")" ::: "memory")
; #define PG8_BAR __builtin_amdgcn_s_barrier()
; #define PG8_SCHED __builtin_amdgcn_sched_barrier(0)
; template <class Epi, class Sched, bool ALIGN_EPI = false, bool SP2 = false, bool F8 = false>
; __device__ __forceinline__ void gemm_phase(PG8_LAS unsigned char* lds, const Gemm g, const Sched& S, const Epi& E) {
;     ...
;             PG8_WAIT_V(8); PG8_WAIT_L(0); PG8_BAR; PG8_MMA(1, 0, At, B0); PG8_MMA(1, 1, At, B1); PG8_BAR; PG8_SCHED;
;             PG8_LDB(B0, 1, 0); PG8_LDB(B1, 1, 1); PG8_SCHED; PG8_LDA(At, 1, 0); PG8_STAGE(PG8_SA(0, 1), a2 + hstep, voffA);
;             PG8_WAIT_V(8); PG8_WAIT_L(0); PG8_BAR; PG8_MMA(0, 0, At, B0); PG8_MMA(0, 1, At, B1); PG8_BAR; PG8_SCHED;
	s_setprio 1
	s_waitcnt lgkmcnt(0)
	v_mfma_f32_16x16x32_bf16 v[60:63], v[140:143], v[184:187], v[60:63]
	v_mfma_f32_16x16x32_bf16 v[56:59], v[156:159], v[184:187], v[56:59]
	v_mfma_f32_16x16x32_bf16 v[44:47], v[140:143], v[192:195], v[44:47]
	v_mfma_f32_16x16x32_bf16 v[40:43], v[156:159], v[192:195], v[40:43]
	v_mfma_f32_16x16x32_bf16 v[28:31], v[140:143], v[200:203], v[28:31]
	v_mfma_f32_16x16x32_bf16 v[24:27], v[156:159], v[200:203], v[24:27]
	v_mfma_f32_16x16x32_bf16 v[12:15], v[140:143], v[208:211], v[12:15]
	v_mfma_f32_16x16x32_bf16 v[8:11], v[156:159], v[208:211], v[8:11]
	v_mfma_f32_16x16x32_bf16 v[60:63], v[152:155], v[188:191], v[60:63]
	v_mfma_f32_16x16x32_bf16 v[56:59], v[164:167], v[188:191], v[56:59]
	v_mfma_f32_16x16x32_bf16 v[44:47], v[152:155], v[196:199], v[44:47]
	v_mfma_f32_16x16x32_bf16 v[40:43], v[164:167], v[196:199], v[40:43]
	v_mfma_f32_16x16x32_bf16 v[28:31], v[152:155], v[204:207], v[28:31]
	v_mfma_f32_16x16x32_bf16 v[24:27], v[164:167], v[204:207], v[24:27]
	v_mfma_f32_16x16x32_bf16 v[12:15], v[152:155], v[212:215], v[12:15]
	v_mfma_f32_16x16x32_bf16 v[8:11], v[164:167], v[212:215], v[8:11]
	v_mfma_f32_16x16x32_bf16 v[52:55], v[168:171], v[184:187], v[52:55]
	v_mfma_f32_16x16x32_bf16 v[48:51], v[176:179], v[184:187], v[48:51]
	v_mfma_f32_16x16x32_bf16 v[36:39], v[168:171], v[192:195], v[36:39]
	v_mfma_f32_16x16x32_bf16 v[32:35], v[176:179], v[192:195], v[32:35]
	v_mfma_f32_16x16x32_bf16 v[20:23], v[168:171], v[200:203], v[20:23]
	v_mfma_f32_16x16x32_bf16 v[16:19], v[176:179], v[200:203], v[16:19]
	v_mfma_f32_16x16x32_bf16 v[4:7], v[168:171], v[208:211], v[4:7]
	v_mfma_f32_16x16x32_bf16 v[0:3], v[176:179], v[208:211], v[0:3]
	v_mfma_f32_16x16x32_bf16 v[52:55], v[172:175], v[188:191], v[52:55]
	v_mfma_f32_16x16x32_bf16 v[48:51], v[180:183], v[188:191], v[48:51]
	v_mfma_f32_16x16x32_bf16 v[36:39], v[172:175], v[196:199], v[36:39]
	v_mfma_f32_16x16x32_bf16 v[32:35], v[180:183], v[196:199], v[32:35]
	v_mfma_f32_16x16x32_bf16 v[20:23], v[172:175], v[204:207], v[20:23]
	v_mfma_f32_16x16x32_bf16 v[16:19], v[180:183], v[204:207], v[16:19]
	v_mfma_f32_16x16x32_bf16 v[4:7], v[172:175], v[212:215], v[4:7]
	v_mfma_f32_16x16x32_bf16 v[0:3], v[180:183], v[212:215], v[0:3]
	s_setprio 0
	s_barrier
	s_add_i32 s57, 0, 0x18000
	v_add_u32_e32 v163, s57, v146
	s_add_i32 s58, 0, 0x1c000
	ds_read_b128 v[140:143], v163
	ds_read_b128 v[152:155], v163 offset:1024
	ds_read_b128 v[156:159], v163 offset:2048
	ds_read_b128 v[164:167], v163 offset:3072
	v_add_u32_e32 v163, s58, v146
	ds_read_b128 v[168:171], v163
	ds_read_b128 v[172:175], v163 offset:1024
	ds_read_b128 v[176:179], v163 offset:2048
	ds_read_b128 v[180:183], v163 offset:3072
	s_add_u32 s38, s38, 0x100000
	s_addc_u32 s39, s39, 0
	s_mov_b32 m0, s43
	v_lshl_add_u64 v[222:223], s[38:39], 0, v[128:129]
	ds_read_b128 v[184:187], v150 offset:32768
	ds_read_b128 v[188:191], v150 offset:33792
	ds_read_b128 v[192:195], v150 offset:34816
	ds_read_b128 v[196:199], v150 offset:35840
	ds_read_b128 v[200:203], v150 offset:36864
	ds_read_b128 v[204:207], v150 offset:37888
	ds_read_b128 v[208:211], v150 offset:38912
	ds_read_b128 v[212:215], v150 offset:39936
	global_load_lds_dwordx4 v[222:223], off
	v_lshl_add_u64 v[222:223], s[38:39], 0, v[130:131]
	s_mov_b32 m0, s44
	s_nop 0
	global_load_lds_dwordx4 v[222:223], off
	s_waitcnt vmcnt(8)
	s_waitcnt lgkmcnt(0)
	s_barrier
	s_setprio 1
	s_waitcnt lgkmcnt(0)
	v_mfma_f32_16x16x32_bf16 v[124:127], v[140:143], v[184:187], v[124:127]
	v_mfma_f32_16x16x32_bf16 v[120:123], v[156:159], v[184:187], v[120:123]
	v_mfma_f32_16x16x32_bf16 v[108:111], v[140:143], v[192:195], v[108:111]
	v_mfma_f32_16x16x32_bf16 v[104:107], v[156:159], v[192:195], v[104:107]
	v_mfma_f32_16x16x32_bf16 v[92:95], v[140:143], v[200:203], v[92:95]
	v_mfma_f32_16x16x32_bf16 v[88:91], v[156:159], v[200:203], v[88:91]
	v_mfma_f32_16x16x32_bf16 v[76:79], v[140:143], v[208:211], v[76:79]
	v_mfma_f32_16x16x32_bf16 v[72:75], v[156:159], v[208:211], v[72:75]
	v_mfma_f32_16x16x32_bf16 v[124:127], v[152:155], v[188:191], v[124:127]
	v_mfma_f32_16x16x32_bf16 v[120:123], v[164:167], v[188:191], v[120:123]
	v_mfma_f32_16x16x32_bf16 v[108:111], v[152:155], v[196:199], v[108:111]
	v_mfma_f32_16x16x32_bf16 v[104:107], v[164:167], v[196:199], v[104:107]
	v_mfma_f32_16x16x32_bf16 v[92:95], v[152:155], v[204:207], v[92:95]
	v_mfma_f32_16x16x32_bf16 v[88:91], v[164:167], v[204:207], v[88:91]
	v_mfma_f32_16x16x32_bf16 v[76:79], v[152:155], v[212:215], v[76:79]
	v_mfma_f32_16x16x32_bf16 v[72:75], v[164:167], v[212:215], v[72:75]
	v_mfma_f32_16x16x32_bf16 v[116:119], v[168:171], v[184:187], v[116:119]
	v_mfma_f32_16x16x32_bf16 v[112:115], v[176:179], v[184:187], v[112:115]
	v_mfma_f32_16x16x32_bf16 v[100:103], v[168:171], v[192:195], v[100:103]
	v_mfma_f32_16x16x32_bf16 v[96:99], v[176:179], v[192:195], v[96:99]
	v_mfma_f32_16x16x32_bf16 v[84:87], v[168:171], v[200:203], v[84:87]
	v_mfma_f32_16x16x32_bf16 v[80:83], v[176:179], v[200:203], v[80:83]
	v_mfma_f32_16x16x32_bf16 v[68:71], v[168:171], v[208:211], v[68:71]
	v_mfma_f32_16x16x32_bf16 v[64:67], v[176:179], v[208:211], v[64:67]
	v_mfma_f32_16x16x32_bf16 v[116:119], v[172:175], v[188:191], v[116:119]
	v_mfma_f32_16x16x32_bf16 v[112:115], v[180:183], v[188:191], v[112:115]
	v_mfma_f32_16x16x32_bf16 v[100:103], v[172:175], v[196:199], v[100:103]
	v_mfma_f32_16x16x32_bf16 v[96:99], v[180:183], v[196:199], v[96:99]
	v_mfma_f32_16x16x32_bf16 v[84:87], v[172:175], v[204:207], v[84:87]
	v_mfma_f32_16x16x32_bf16 v[80:83], v[180:183], v[204:207], v[80:83]
	v_mfma_f32_16x16x32_bf16 v[68:71], v[172:175], v[212:215], v[68:71]
	v_mfma_f32_16x16x32_bf16 v[64:67], v[180:183], v[212:215], v[64:67]
	s_setprio 0
	s_barrier
; #define PG8_STAGE(bufoff, gbase, voff) do { _Pragma("unroll") for (int _i = 0; _i < 2; ++_i) \
;         __builtin_amdgcn_global_load_lds((const unsigned*)((const char*)(gbase) + (voff)[_i]), (PG8_LAS unsigned*)(lds + (bufoff) + ldsw + _i * 8192), 16, 0, 0); } while (0)
; #define PG8_WAIT_V(n) asm volatile("s_waitcnt vmcnt(" #n ")" ::: "memory")
; #define PG8_WAIT_L(n) asm volatile("s_waitcnt lgkmcnt(" #n ")" ::: "memory")
; #define PG8_BAR __builtin_amdgcn_s_barrier()
; #define PG8_SCHED __builtin_amdgcn_sched_barrier(0)
; template <class Epi, class Sched, bool ALIGN_EPI = false, bool SP2 = false, bool F8 = false>
; __device__ __forceinline__ void gemm_phase(PG8_LAS unsigned char* lds, const Gemm g, const Sched& S, const Epi& E) {
;     ...
;             PG8_LDA(At, 1, 1); PG8_STAGE(PG8_SB(1, 0), b3, voffB); PG8_STAGE(PG8_SB(1, 1), b3 + hstep, voffB); PG8_STAGE(PG8_SA(1, 0), a3, voffA);
;             PG8_WAIT_V(8); PG8_WAIT_L(0); PG8_BAR; PG8_MMA(1, 0, At, B0); PG8_MMA(1, 1, At, B1); PG8_BAR; PG8_SCHED;
	s_add_i32 s38, s57, s41
	v_lshl_add_u64 v[160:161], v[160:161], 0, s[16:17]
	s_mov_b32 m0, s38
	ds_read_b128 v[184:187], v150 offset:49152
	ds_read_b128 v[188:191], v150 offset:50176
	ds_read_b128 v[192:195], v150 offset:51200
	ds_read_b128 v[196:199], v150 offset:52224
	ds_read_b128 v[200:203], v150 offset:53248
	ds_read_b128 v[204:207], v150 offset:54272
	ds_read_b128 v[208:211], v150 offset:55296
	ds_read_b128 v[212:215], v150 offset:56320
	global_load_lds_dwordx4 v[160:161], off
	s_add_i32 m0, s38, 0x2000
	s_add_u32 s36, s36, 0x100080
	v_lshl_add_u64 v[160:161], v[216:217], 0, s[16:17]
	s_addc_u32 s37, s37, 0
	s_add_i32 s38, s58, s41
	global_load_lds_dwordx4 v[160:161], off
	v_lshl_add_u64 v[160:161], s[36:37], 0, v[128:129]
	s_mov_b32 m0, s38
	s_nop 0
	global_load_lds_dwordx4 v[160:161], off
	v_lshl_add_u64 v[160:161], s[36:37], 0, v[130:131]
	s_add_i32 m0, s38, 0x2000
	s_nop 0
	global_load_lds_dwordx4 v[160:161], off
	v_lshl_add_u64 v[160:161], v[218:219], 0, s[16:17]
	s_mov_b32 m0, s46
	s_nop 0
	global_load_lds_dwordx4 v[160:161], off
	v_lshl_add_u64 v[160:161], v[220:221], 0, s[16:17]
	s_mov_b32 m0, s47
	s_nop 0
	global_load_lds_dwordx4 v[160:161], off
	s_waitcnt vmcnt(8)
	s_waitcnt lgkmcnt(0)
	s_barrier
	s_setprio 1
	s_waitcnt lgkmcnt(0)
	v_mfma_f32_16x16x32_bf16 v[60:63], v[140:143], v[184:187], v[60:63]
	v_mfma_f32_16x16x32_bf16 v[56:59], v[156:159], v[184:187], v[56:59]
	v_mfma_f32_16x16x32_bf16 v[44:47], v[140:143], v[192:195], v[44:47]
	v_mfma_f32_16x16x32_bf16 v[40:43], v[156:159], v[192:195], v[40:43]
	v_mfma_f32_16x16x32_bf16 v[28:31], v[140:143], v[200:203], v[28:31]
	v_mfma_f32_16x16x32_bf16 v[24:27], v[156:159], v[200:203], v[24:27]
	v_mfma_f32_16x16x32_bf16 v[12:15], v[140:143], v[208:211], v[12:15]
	v_mfma_f32_16x16x32_bf16 v[8:11], v[156:159], v[208:211], v[8:11]
	v_mfma_f32_16x16x32_bf16 v[60:63], v[152:155], v[188:191], v[60:63]
	v_mfma_f32_16x16x32_bf16 v[56:59], v[164:167], v[188:191], v[56:59]
	v_mfma_f32_16x16x32_bf16 v[44:47], v[152:155], v[196:199], v[44:47]
	v_mfma_f32_16x16x32_bf16 v[40:43], v[164:167], v[196:199], v[40:43]
	v_mfma_f32_16x16x32_bf16 v[28:31], v[152:155], v[204:207], v[28:31]
	v_mfma_f32_16x16x32_bf16 v[24:27], v[164:167], v[204:207], v[24:27]
	v_mfma_f32_16x16x32_bf16 v[12:15], v[152:155], v[212:215], v[12:15]
	v_mfma_f32_16x16x32_bf16 v[8:11], v[164:167], v[212:215], v[8:11]
	v_mfma_f32_16x16x32_bf16 v[52:55], v[168:171], v[184:187], v[52:55]
	v_mfma_f32_16x16x32_bf16 v[48:51], v[176:179], v[184:187], v[48:51]
	v_mfma_f32_16x16x32_bf16 v[36:39], v[168:171], v[192:195], v[36:39]
	v_mfma_f32_16x16x32_bf16 v[32:35], v[176:179], v[192:195], v[32:35]
	v_mfma_f32_16x16x32_bf16 v[20:23], v[168:171], v[200:203], v[20:23]
	v_mfma_f32_16x16x32_bf16 v[16:19], v[176:179], v[200:203], v[16:19]
	v_mfma_f32_16x16x32_bf16 v[4:7], v[168:171], v[208:211], v[4:7]
	v_mfma_f32_16x16x32_bf16 v[0:3], v[176:179], v[208:211], v[0:3]
	v_mfma_f32_16x16x32_bf16 v[52:55], v[172:175], v[188:191], v[52:55]
	v_mfma_f32_16x16x32_bf16 v[48:51], v[180:183], v[188:191], v[48:51]
	v_mfma_f32_16x16x32_bf16 v[36:39], v[172:175], v[196:199], v[36:39]
	v_mfma_f32_16x16x32_bf16 v[32:35], v[180:183], v[196:199], v[32:35]
	v_mfma_f32_16x16x32_bf16 v[20:23], v[172:175], v[204:207], v[20:23]
	v_mfma_f32_16x16x32_bf16 v[16:19], v[180:183], v[204:207], v[16:19]
	v_mfma_f32_16x16x32_bf16 v[4:7], v[172:175], v[212:215], v[4:7]
	v_mfma_f32_16x16x32_bf16 v[0:3], v[180:183], v[212:215], v[0:3]
	s_setprio 0
	s_barrier
	s_add_i32 s56, s56, 2
	s_add_u32 s34, s34, 0x100
	s_addc_u32 s35, s35, 0
	s_add_u32 s54, s54, 0x100
	s_addc_u32 s55, s55, 0
	s_cmp_gt_u32 s56, 61
	s_cbranch_scc0 .LBB0_644
	s_and_b64 vcc, exec, s[18:19]
	s_cbranch_vccz .LBB0_647
	s_barrier
